# attention fast paths: one static s_setprio 1 for waves 4-7 around each loop
# baseline (speedup 1.0000x reference)
; template <int MODE>
; DI void attn_item(const Params& p, int layer, int bh, int qb, char* lds) {
;     ...
;     b = bh / 6; hd = bh % 6;
;     const u16* Hb = (const u16*)(p.ws + OFF_H) + (size_t)b * S * DIN;
;     Qg = Hb + C_SQ + hd * 64; qstr = DIN; kstr = vstr = 64;
;     Kg = (const u16*)(p.ws + OFF_SK) + (size_t)(b * 2 + hd / 3) * S * 64; Vg = (const u16*)(p.ws + OFF_SV) + (size_t)(b * 2 + hd / 3) * S * 64;
;     ocol = 640 + hd * 64;
;   }
;   float* brel = (float*)lds;
;   char* stage0 = lds + BREL_BYTES;
;   if (MODE != 0) {
;     const int bcol = MODE == 1 ? hd : 4 + hd;
;     for (int i = tid; i < 512; i += NTHR) {
;       int rel = i - 224, rc = rel < -128 ? -128 : (rel > 128 ? 128 : rel);
;       float bv = p.relb[t5_bucket(rc) * 10 + bcol] * LOG2E;
;       brel[i] = (MODE == 2 && rc != rel) ? -1e30f : bv;
;     }
;   }
;   bf16x8 qf[NMAP][QS];
;   {
;     const u16* qrow = Qg + (size_t)(q0w + l32) * qstr + hh * 8;
; #pragma unroll
;     for (int mp = 0; mp < NMAP; ++mp)
; #pragma unroll
;       for (int st = 0; st < QS; ++st) qf[mp][st] = *(const bf16x8*)(qrow + (mp * QS + st) * 16);
;   }
;   f32x16 O[NMAP][2]; float m = 0.f, l[NMAP];
; #pragma unroll
;   for (int mp = 0; mp < NMAP; ++mp) {
; #pragma unroll
;     for (int r = 0; r < 16; ++r) { O[mp][0][r] = 0.f; O[mp][1][r] = 0.f; }
;     l[mp] = 0.f;
;   }
;   if (MODE == 2) { m = p.sink[layer * 6 + hd] * LOG2E; l[0] = (hh == 0) ? 1.f : 0.f; }
;   int kt0 = 0, kt1 = S / 64;
;   if (MODE == 2) { kt0 = (q0 - 128) / 64; if (kt0 < 0) kt0 = 0; kt1 = (q0 + 384) / 64; if (kt1 > S / 64) kt1 = S / 64; }
;   const int nt = kt1 - kt0;
;   constexpr int KSTRG = MODE == 0 ? 96 : 64, VSTRG = 64;
;   u32x4 rkA[KCH], rvA[1], rkB[KCH], rvB[1];
;   const __amdgpu_buffer_rsrc_t krsrc = __builtin_amdgcn_make_buffer_rsrc((void*)Kg, 0, S * KSTRG * 2, 0x00027000);
;   const __amdgpu_buffer_rsrc_t vrsrc = __builtin_amdgcn_make_buffer_rsrc((void*)Vg, 0, S * VSTRG * 2, 0x00027000);
;   auto gload = [&](int kt, u32x4 (&rk)[KCH], u32x4 (&rv)[1]) {
;     const int ksoff = kt * (64 * KSTRG * 2), vsoff = kt * (64 * VSTRG * 2);
; #pragma unroll
;     for (int i = 0; i < KCH; ++i) if (tid + NTHR * i < KCHUNKS) rk[i] = __builtin_amdgcn_raw_buffer_load_b128(krsrc, tid * 16 + NTHR * 16 * i, ksoff, 0);
;     rv[0] = __builtin_amdgcn_raw_buffer_load_b128(vrsrc, tid * 16, vsoff, 0);
;   };
.LBB0_334:
	s_or_b64 exec, exec, s[8:9]
	s_and_b32 s9, 0xffff, s21
	s_mul_i32 s6, s9, 0x2b80000
	s_add_u32 s6, s34, s6
	s_addc_u32 s7, s35, 0
	s_lshl_b32 s8, s20, 7
	s_add_u32 s6, s6, s8
	s_addc_u32 s7, s7, 0
	s_add_u32 s6, s6, 0x60589c0
	v_ashrrev_i32_e32 v1, 1, v0
	s_addc_u32 s7, s7, 0
	v_and_b32_e32 v1, 0xffffffe0, v1
	s_cmp_gt_u32 s20, 2
	v_and_b32_e32 v222, 31, v0
	v_add_u32_e32 v186, s23, v1
	s_cselect_b32 s8, 0x100000, 0
	s_lshl_b32 s10, s9, 21
	s_or_b32 s8, s10, s8
	v_readlane_b32 s10, v254, 37
	v_or_b32_e32 v3, v186, v222
	v_mov_b64_e32 v[6:7], s[6:7]
	v_readlane_b32 s11, v254, 38
	s_add_u32 s24, s10, s8
	v_mad_i64_i32 v[6:7], s[6:7], v3, s64, v[6:7]
	s_addc_u32 s10, s11, 0
	v_readlane_b32 s12, v254, 35
	v_readlane_b32 s6, v255, 40
	v_bfe_u32 v2, v0, 5, 1
	v_readlane_b32 s13, v254, 36
	s_add_u32 s12, s12, s8
	s_mul_i32 s6, s6, 6
	s_addc_u32 s11, s13, 0
	v_lshlrev_b32_e32 v188, 4, v2
	v_mov_b32_e32 v189, v5
	v_readlane_b32 s7, v255, 41
	s_add_i32 s52, s6, s20
	v_lshl_add_u64 v[6:7], v[6:7], 0, v[188:189]
	s_lshl_b64 s[6:7], s[52:53], 2
	global_load_dwordx4 v[112:115], v[6:7], off
	global_load_dwordx4 v[116:119], v[6:7], off offset:32
	global_load_dwordx4 v[120:123], v[6:7], off offset:64
	global_load_dwordx4 v[124:127], v[6:7], off offset:96
	s_add_u32 s6, s80, s6
	s_addc_u32 s7, s81, s7
	global_load_dword v3, v5, s[6:7]
	s_add_i32 s6, s23, 0xffffff80
	s_ashr_i32 s6, s6, 6
	v_mov_b32_e32 v6, v5
	v_mov_b32_e32 v7, v5
	s_max_i32 s8, s6, 0
	v_mov_b32_e32 v4, v5
	v_mov_b64_e32 v[130:131], v[6:7]
	s_and_b32 s25, s10, 0xffff
	s_lshl_b32 s10, s8, 13
	v_lshlrev_b32_e32 v187, 4, v0
	v_mov_b64_e32 v[128:129], v[4:5]
	s_waitcnt lgkmcnt(0)
	s_barrier
	s_and_b32 s13, s11, 0xffff
	s_mov_b32 s26, s14
	s_mov_b32 s27, s15
	s_lshl_b32 s52, s9, 13
	s_lshl_b32 s63, s20, 6
	s_mov_b32 s93, s10
	s_mov_b32 s28, s8
	s_add_i32 s29, s23, 0x180
	s_lshr_b32 s29, s29, 6
	s_min_u32 s29, s29, 0x80
	s_sub_u32 s62, s29, s8
	v_readfirstlane_b32 s49, v186
	s_nop 0
	s_add_i32 s10, s49, 0xffffff80
	s_ashr_i32 s10, s10, 6
	s_max_i32 s10, s10, s8
	s_add_i32 s11, s49, 0x9f
	s_lshr_b32 s11, s11, 6
	s_add_u32 s11, s11, 1
	s_min_u32 s11, s11, s29
	v_bfe_u32 v15, v184, 5, 1
	v_lshlrev_b32_e32 v189, 2, v15
	v_mov_b32_e32 v200, 144
	v_mul_u32_u24_e32 v206, v222, v200
	v_lshl_add_u32 v206, v15, 4, v206
	v_bfe_u32 v200, v184, 2, 2
	v_lshl_add_u32 v200, v15, 2, v200
	v_mov_b32_e32 v201, 192
	v_mul_u32_u24_e32 v207, v200, v201
	v_bfe_u32 v200, v184, 4, 1
	v_lshl_add_u32 v207, v200, 5, v207
	v_and_b32_e32 v200, 3, v184
	v_lshl_add_u32 v207, v200, 3, v207
	v_lshrrev_b32_e32 v14, 3, v184
	v_and_b32_e32 v200, 7, v184
	v_mov_b32_e32 v201, 144
	v_mul_u32_u24_e32 v208, v14, v201
	v_lshl_add_u32 v208, v200, 4, v208
	v_mov_b32_e32 v201, 192
	v_mul_u32_u24_e32 v209, v14, v201
	v_lshl_add_u32 v209, v200, 4, v209
	v_cmp_eq_u32_e64 s[6:7], 0, v15
	v_sub_u32_e32 v14, v189, v222
	v_sub_u32_e32 v14, v14, v186
	v_add_u32_e32 v14, 0xe0, v14
	v_lshlrev_b32_e32 v210, 2, v14
	buffer_load_dwordx4 v[128:131], v187, s[24:27], s93 offen
	buffer_load_dwordx4 v[132:135], v187, s[12:15], s93 offen
	s_add_u32 s93, s93, 0x2000
	buffer_load_dwordx4 v[248:251], v187, s[24:27], s93 offen
	buffer_load_dwordx4 v[224:227], v187, s[12:15], s93 offen
	s_add_u32 s93, s93, 0x2000
	s_waitcnt vmcnt(2)
	ds_write_b128 v208, v[128:131] offset:2048
	ds_write_b128 v209, v[132:135] offset:11264
	v_mul_f32_e32 v204, 0x3fb8aa3b, v3
	v_cndmask_b32_e64 v231, 0, 1.0, s[6:7]
	v_sub_f32_e32 v200, 0, v204
	v_bfe_u32 v15, v200, 16, 1
	v_add3_u32 v14, v200, v15, s45
	v_lshrrev_b32_e32 v15, 16, v14
	v_and_b32_e32 v14, 0xffff0000, v14
	v_sub_f32_e32 v14, v200, v14
	v_bfe_u32 v200, v14, 16, 1
	v_add3_u32 v14, v14, v200, s45
	v_and_or_b32 v14, v14, s92, v15
	v_cndmask_b32_e64 v140, 0, v14, s[6:7]
	v_mov_b32_e32 v14, 0x3f803f80
	v_cndmask_b32_e64 v136, 0, v14, s[6:7]
	v_mov_b32_e32 v137, 0
	v_mov_b32_e32 v141, 0
	v_mov_b32_e32 v138, 0
	v_mov_b32_e32 v142, 0
	v_mov_b32_e32 v139, 0
	v_mov_b32_e32 v143, 0
	s_nop 1
	v_mfma_f32_32x32x16_bf16 v[48:63], v[136:139], v[140:143], 0
	v_mov_b32_e32 v16, 0
	v_mov_b32_e32 v32, 0
	v_mov_b32_e32 v17, 0
	v_mov_b32_e32 v33, 0
	v_mov_b32_e32 v18, 0
	v_mov_b32_e32 v34, 0
	v_mov_b32_e32 v19, 0
	v_mov_b32_e32 v35, 0
	v_mov_b32_e32 v20, 0
	v_mov_b32_e32 v36, 0
	v_mov_b32_e32 v21, 0
	v_mov_b32_e32 v37, 0
	v_mov_b32_e32 v22, 0
	v_mov_b32_e32 v38, 0
	v_mov_b32_e32 v23, 0
	v_mov_b32_e32 v39, 0
	v_mov_b32_e32 v24, 0
	v_mov_b32_e32 v40, 0
	v_mov_b32_e32 v25, 0
	v_mov_b32_e32 v41, 0
	v_mov_b32_e32 v26, 0
	v_mov_b32_e32 v42, 0
	v_mov_b32_e32 v27, 0
	v_mov_b32_e32 v43, 0
	v_mov_b32_e32 v28, 0
	v_mov_b32_e32 v44, 0
	v_mov_b32_e32 v29, 0
	v_mov_b32_e32 v45, 0
	v_mov_b32_e32 v30, 0
	v_mov_b32_e32 v46, 0
	v_mov_b32_e32 v31, 0
	v_mov_b32_e32 v47, 0
	v_mov_b32_e32 v205, 0
	s_waitcnt lgkmcnt(0)
	s_barrier
	v_readfirstlane_b32 s29, v184
	s_nop 3
	s_cmpk_ge_u32 s29, 0x100
	s_cbranch_scc0 .Lsw_prio
	s_setprio 1
; template <int MODE>
; DI void attn_item(const Params& p, int layer, int bh, int qb, char* lds) {
;     ...
; #pragma unroll
;           for (int st = 0; st < QS; ++st) {
;             bf16x8 kf = *(const bf16x8*)(Ks + (32 * sub + l32) * KSTR + ((mp * QS + st) * 16 + hh * 8) * 2);
;             if (st == 0) s[sub] = MFMA(kf, qf[mp][st], c0tile); else s[sub] = MFMA(kf, qf[mp][st], s[sub]);
;           }
;         }
;         __builtin_amdgcn_iglp_opt(1);
;         __builtin_amdgcn_s_setprio(0);
;         if (NMAP == 1) {
;           lds_s16x4* vb = (lds_s16x4*)(Ks + KBYTES + vlane);
; #pragma unroll
;           for (int i = 0; i < 16; ++i) {
;             const int sub_ = i >> 3, ks_ = (i >> 2) & 1, dt_ = (i >> 1) & 1, g_ = i & 1;
;             vpre[i] = __builtin_amdgcn_ds_read_tr16_b64_v4i16(vb + ((32 * sub_ + 16 * ks_ + 8 * g_) * VSTR + 64 * dt_) / 8);
;           }
;           __builtin_amdgcn_sched_barrier(0);
;         }
;         if (MODE != 0 && !far) {
; #pragma unroll
;           for (int sub = 0; sub < 2; ++sub)
; #pragma unroll
;             for (int r = 0; r < 16; ++r) s[sub][r] += brow[32 * sub + (r & 3) + 8 * (r >> 2)];
;         }
;         const bool first = (MODE != 2) && (t == 0) && (mp == 0);
;         auto rebase = [&]() {
;           float mx = fmaxf(fmaxf(s[0][0], s[0][1]), s[0][2]);
; #pragma unroll
;           for (int r = 3; r < 15; r += 2) mx = fmaxf(fmaxf(mx, s[0][r]), s[0][r + 1]);
;           mx = fmaxf(mx, s[0][15]);
; #pragma unroll
;           for (int r = 0; r < 16; r += 2) mx = fmaxf(fmaxf(mx, s[1][r]), s[1][r + 1]);
;           const float rm = xchg_max(mx);
;           float delta = first ? rm : fmaxf(rm, 0.f);
;           if (delta < -1e29f) delta = 0.f;
;           m += delta;
;           const float alpha = __builtin_amdgcn_exp2f(-delta);
; #pragma unroll
;           for (int mq = 0; mq < NMAP; ++mq) {
;             l[mq] *= alpha;
; #pragma unroll
;             for (int r = 0; r < 16; ++r) { O[mq][0][r] *= alpha; O[mq][1][r] *= alpha; }
;           }
; #pragma unroll
;           for (int r = 0; r < 16; ++r) { s[0][r] -= delta; s[1][r] -= delta; }
;           set_c0(cb - m);
;         };
;         float ps;
;         auto smpass = [&]() {
;           ps = 0.f;
; #pragma unroll
;           for (int sub = 0; sub < 2; ++sub)
; #pragma unroll
;             for (int ks = 0; ks < 2; ++ks)
; #pragma unroll
.Lsw_prio:
.Lsw_loop:
	s_cmp_ge_u32 s28, s10
	s_cbranch_scc0 .Lsw_skip_a
	s_cmp_lt_u32 s28, s11
	s_cbranch_scc0 .Lsw_skip_a
	s_lshl_b32 s29, s28, 8
	v_add_u32_e32 v200, s29, v210
	ds_read_b128 v[232:235], v206 offset:2048
	ds_read_b128 v[236:239], v206 offset:2080
	ds_read_b128 v[240:243], v206 offset:2112
	ds_read_b128 v[244:247], v206 offset:2144
	s_waitcnt lgkmcnt(3)
	v_mfma_f32_32x32x16_bf16 v[64:79], v[232:235], v[112:115], v[48:63]
	ds_read_b128 v[232:235], v206 offset:6656
	ds_read2_b32 v[128:129], v200 offset0:0 offset1:1
	ds_read2_b32 v[130:131], v200 offset0:2 offset1:3
	s_waitcnt lgkmcnt(5)
	v_mfma_f32_32x32x16_bf16 v[64:79], v[236:239], v[116:119], v[64:79]
	ds_read_b128 v[236:239], v206 offset:6688
	ds_read2_b32 v[132:133], v200 offset0:8 offset1:9
	ds_read2_b32 v[134:135], v200 offset0:10 offset1:11
	s_waitcnt lgkmcnt(7)
	v_mfma_f32_32x32x16_bf16 v[64:79], v[240:243], v[120:123], v[64:79]
	ds_read_b128 v[240:243], v206 offset:6720
	ds_read2_b32 v[136:137], v200 offset0:16 offset1:17
	ds_read2_b32 v[138:139], v200 offset0:18 offset1:19
	s_waitcnt lgkmcnt(9)
	v_mfma_f32_32x32x16_bf16 v[64:79], v[244:247], v[124:127], v[64:79]
	ds_read_b128 v[244:247], v206 offset:6752
	ds_read2_b32 v[140:141], v200 offset0:24 offset1:25
	ds_read2_b32 v[142:143], v200 offset0:26 offset1:27
	s_waitcnt lgkmcnt(11)
	v_mfma_f32_32x32x16_bf16 v[80:95], v[232:235], v[112:115], v[48:63]
	ds_read2_b32 v[144:145], v200 offset0:32 offset1:33
	ds_read2_b32 v[146:147], v200 offset0:34 offset1:35
	s_waitcnt lgkmcnt(10)
	v_mfma_f32_32x32x16_bf16 v[80:95], v[236:239], v[116:119], v[80:95]
	ds_read2_b32 v[148:149], v200 offset0:40 offset1:41
	ds_read2_b32 v[150:151], v200 offset0:42 offset1:43
	s_waitcnt lgkmcnt(9)
	v_mfma_f32_32x32x16_bf16 v[80:95], v[240:243], v[120:123], v[80:95]
	ds_read2_b32 v[152:153], v200 offset0:48 offset1:49
	ds_read2_b32 v[154:155], v200 offset0:50 offset1:51
	s_waitcnt lgkmcnt(8)
	v_mfma_f32_32x32x16_bf16 v[80:95], v[244:247], v[124:127], v[80:95]
	ds_read2_b32 v[156:157], v200 offset0:56 offset1:57
	ds_read2_b32 v[158:159], v200 offset0:58 offset1:59
	s_waitcnt lgkmcnt(0)
	ds_read_b64_tr_b16 v[160:161], v207 offset:11264
	ds_read_b64_tr_b16 v[162:163], v207 offset:12800
	ds_read_b64_tr_b16 v[164:165], v207 offset:11328
	ds_read_b64_tr_b16 v[166:167], v207 offset:12864
	ds_read_b64_tr_b16 v[168:169], v207 offset:14336
	ds_read_b64_tr_b16 v[170:171], v207 offset:15872
	ds_read_b64_tr_b16 v[172:173], v207 offset:14400
	ds_read_b64_tr_b16 v[174:175], v207 offset:15936
	v_add_f32_e32 v64, v64, v128
	v_add_f32_e32 v65, v65, v129
	v_add_f32_e32 v66, v66, v130
	v_add_f32_e32 v67, v67, v131
	v_add_f32_e32 v68, v68, v132
	v_add_f32_e32 v69, v69, v133
	v_add_f32_e32 v70, v70, v134
	v_add_f32_e32 v71, v71, v135
	v_add_f32_e32 v72, v72, v136
	v_add_f32_e32 v73, v73, v137
	v_add_f32_e32 v74, v74, v138
	v_add_f32_e32 v75, v75, v139
	v_add_f32_e32 v76, v76, v140
	v_add_f32_e32 v77, v77, v141
	v_add_f32_e32 v78, v78, v142
	v_add_f32_e32 v79, v79, v143
	v_add_f32_e32 v80, v80, v144
	v_add_f32_e32 v81, v81, v145
	v_add_f32_e32 v82, v82, v146
	v_add_f32_e32 v83, v83, v147
	v_add_f32_e32 v84, v84, v148
	v_add_f32_e32 v85, v85, v149
	v_add_f32_e32 v86, v86, v150
	v_add_f32_e32 v87, v87, v151
	v_add_f32_e32 v88, v88, v152
	v_add_f32_e32 v89, v89, v153
	v_add_f32_e32 v90, v90, v154
	v_add_f32_e32 v91, v91, v155
	v_add_f32_e32 v92, v92, v156
	v_add_f32_e32 v93, v93, v157
	v_add_f32_e32 v94, v94, v158
	v_add_f32_e32 v95, v95, v159
	s_waitcnt lgkmcnt(4)
	ds_read_b64_tr_b16 v[176:177], v207 offset:17408
	ds_read_b64_tr_b16 v[178:179], v207 offset:18944
	ds_read_b64_tr_b16 v[180:181], v207 offset:17472
	ds_read_b64_tr_b16 v[182:183], v207 offset:19008
	ds_read_b64_tr_b16 v[192:193], v207 offset:20480
	ds_read_b64_tr_b16 v[194:195], v207 offset:22016
	ds_read_b64_tr_b16 v[196:197], v207 offset:20544
	ds_read_b64_tr_b16 v[198:199], v207 offset:22080
	v_exp_f32_e32 v0, v64
	v_exp_f32_e32 v1, v65
	v_exp_f32_e32 v2, v66
	v_exp_f32_e32 v3, v67
	v_add_f32_e32 v10, v0, v1
	v_cvt_pk_bf16_f32 v96, v0, v1
	v_add_f32_e32 v10, v10, v2
	v_add_f32_e32 v10, v10, v3
	v_cvt_pk_bf16_f32 v97, v2, v3
	v_exp_f32_e32 v6, v68
	v_exp_f32_e32 v7, v69
	v_exp_f32_e32 v8, v70
	v_exp_f32_e32 v9, v71
	v_add_f32_e32 v10, v10, v6
	v_add_f32_e32 v10, v10, v7
	v_cvt_pk_bf16_f32 v98, v6, v7
	v_add_f32_e32 v10, v10, v8
	v_add_f32_e32 v10, v10, v9
	v_cvt_pk_bf16_f32 v99, v8, v9
	v_exp_f32_e32 v0, v72
	v_exp_f32_e32 v1, v73
	v_exp_f32_e32 v2, v74
	v_exp_f32_e32 v3, v75
	v_add_f32_e32 v11, v0, v1
	v_cvt_pk_bf16_f32 v100, v0, v1
	v_add_f32_e32 v11, v11, v2
	v_add_f32_e32 v11, v11, v3
	v_cvt_pk_bf16_f32 v101, v2, v3
	v_exp_f32_e32 v6, v76
	v_exp_f32_e32 v7, v77
	v_exp_f32_e32 v8, v78
	v_exp_f32_e32 v9, v79
	v_add_f32_e32 v11, v11, v6
	v_add_f32_e32 v11, v11, v7
	v_cvt_pk_bf16_f32 v102, v6, v7
	v_add_f32_e32 v11, v11, v8
	v_add_f32_e32 v11, v11, v9
	v_cvt_pk_bf16_f32 v103, v8, v9
	v_exp_f32_e32 v0, v80
	v_exp_f32_e32 v1, v81
	v_exp_f32_e32 v2, v82
	v_exp_f32_e32 v3, v83
	v_add_f32_e32 v12, v0, v1
	v_cvt_pk_bf16_f32 v104, v0, v1
	v_add_f32_e32 v12, v12, v2
	v_add_f32_e32 v12, v12, v3
	v_cvt_pk_bf16_f32 v105, v2, v3
	v_exp_f32_e32 v6, v84
	v_exp_f32_e32 v7, v85
	v_exp_f32_e32 v8, v86
	v_exp_f32_e32 v9, v87
	v_add_f32_e32 v12, v12, v6
	v_add_f32_e32 v12, v12, v7
	v_cvt_pk_bf16_f32 v106, v6, v7
	v_add_f32_e32 v12, v12, v8
	v_add_f32_e32 v12, v12, v9
	v_cvt_pk_bf16_f32 v107, v8, v9
	v_exp_f32_e32 v0, v88
	v_exp_f32_e32 v1, v89
	v_exp_f32_e32 v2, v90
	v_exp_f32_e32 v3, v91
	v_add_f32_e32 v13, v0, v1
	v_cvt_pk_bf16_f32 v108, v0, v1
	v_add_f32_e32 v13, v13, v2
	v_add_f32_e32 v13, v13, v3
	v_cvt_pk_bf16_f32 v109, v2, v3
	v_exp_f32_e32 v6, v92
	v_exp_f32_e32 v7, v93
	v_exp_f32_e32 v8, v94
	v_exp_f32_e32 v9, v95
	v_add_f32_e32 v13, v13, v6
	v_add_f32_e32 v13, v13, v7
	v_cvt_pk_bf16_f32 v110, v6, v7
	v_add_f32_e32 v13, v13, v8
	v_add_f32_e32 v13, v13, v9
	v_cvt_pk_bf16_f32 v111, v8, v9
	v_add_f32_e32 v10, v10, v11
	v_add_f32_e32 v12, v12, v13
	v_add_f32_e32 v10, v10, v12
	v_add_f32_e32 v231, v231, v10
	v_max_f32_e32 v205, v205, v10
	v_mfma_f32_32x32x16_bf16 v[32:47], v[160:163], v[96:99], v[32:47]
	v_mfma_f32_32x32x16_bf16 v[16:31], v[164:167], v[96:99], v[16:31]
	s_waitcnt lgkmcnt(10)
	v_mfma_f32_32x32x16_bf16 v[32:47], v[168:171], v[100:103], v[32:47]
	s_waitcnt lgkmcnt(8)
	v_mfma_f32_32x32x16_bf16 v[16:31], v[172:175], v[100:103], v[16:31]
	s_waitcnt lgkmcnt(6)
	v_mfma_f32_32x32x16_bf16 v[32:47], v[176:179], v[104:107], v[32:47]
	s_waitcnt lgkmcnt(4)
	v_mfma_f32_32x32x16_bf16 v[16:31], v[180:183], v[104:107], v[16:31]
	s_waitcnt lgkmcnt(2)
	v_mfma_f32_32x32x16_bf16 v[32:47], v[192:195], v[108:111], v[32:47]
	s_waitcnt lgkmcnt(0)
	v_mfma_f32_32x32x16_bf16 v[16:31], v[196:199], v[108:111], v[16:31]

; #define LDS_BARRIER() asm volatile("s_waitcnt lgkmcnt(0)\n\ts_barrier" ::: "memory")
; template <int MODE>
; DI void attn_item(const Params& p, int layer, int bh, int qb, char* lds) {
;     ...
;         if (first) rebase();
;         smpass();
;         if (!first && __any(!(ps <= PSLIM))) { rebase(); smpass(); }
;         l[mp] += ps;
;     ...
;   for (int t = 0; t < nt; t += 2) {
;     if (t + 2 < nt) gload(kt0 + t + 2, rkA, rvA);
;     compute(t, 0);
;     if (t + 1 < nt) lstore(1, rkB, rvB);
;     LDS_BARRIER();
;     if (t + 1 >= nt) break;
;     if (t + 3 < nt) gload(kt0 + t + 3, rkB, rvB);
;     compute(t + 1, 1);
;     if (t + 2 < nt) lstore(0, rkA, rvA);
;     LDS_BARRIER();
;   }
.Lsw_exit:
	s_setprio 0
	s_waitcnt vmcnt(0)
	v_cmp_nge_f32_e32 vcc, s94, v205
	s_nop 0
	s_cmp_lg_u64 vcc, 0
	s_cselect_b32 s29, 1, 0
	v_mov_b32_e32 v14, s29
	v_lshrrev_b32_e32 v15, 6, v184
	v_lshlrev_b32_e32 v15, 2, v15
	v_add_u32_e32 v15, 45056, v15
	ds_write_b32 v15, v14
	s_waitcnt lgkmcnt(0)
	s_barrier
	v_mov_b32_e32 v15, 45056
	ds_read_b128 v[232:235], v15
	ds_read_b128 v[236:239], v15 offset:16
	s_waitcnt lgkmcnt(0)
	v_or3_b32 v14, v232, v233, v234
	v_or3_b32 v14, v14, v235, v236
	v_or3_b32 v14, v14, v237, v238
	v_or_b32_e32 v14, v14, v239
	s_nop 0
	v_readfirstlane_b32 s29, v14
	s_nop 11
	s_cmp_lg_u32 s29, 0
	s_cbranch_scc0 .LBB0_389
	s_barrier
	v_mov_b32_e32 v0, v184
	v_readlane_b32 s63, v255, 39
	s_mov_b64 s[4:5], -1
	s_mov_b64 s[8:9], -1
	s_branch .Lswa_slow

; template <int MODE>
; DI void attn_item(const Params& p, int layer, int bh, int qb, char* lds) {
;     ...
;   if (MODE == 0) {
;     b = bh / 6; hd = bh % 6;
;     Qg = (const u16*)(p.ws + OFF_QB) + (size_t)b * S * QW + hd * 96; qstr = QW;
;     Kg = (const u16*)(p.ws + OFF_KB) + (size_t)(b * 6 + hd) * S * 96; kstr = 96;
;     Vg = (const u16*)(p.ws + OFF_VB) + (size_t)(b * 6 + hd) * S * 64; vstr = 64;
;     ocol = hd * 64;
;   } else if (MODE == 1) {
;     b = bh / 4; hd = bh % 4;
;     const u16* Hb = (const u16*)(p.ws + OFF_H) + (size_t)b * S * DIN;
;     Qg = Hb + C_DQ + hd * 64; qstr = DIN; kstr = vstr = 64;
;     Kg = (const u16*)(p.ws + OFF_DK) + (size_t)(b * 4 + hd) * S * 64; Vg = (const u16*)(p.ws + OFF_DV) + (size_t)(b * 4 + hd) * S * 64;
;     ocol = 384 + hd * 64;
;   } else {
;     b = bh / 6; hd = bh % 6;
;     const u16* Hb = (const u16*)(p.ws + OFF_H) + (size_t)b * S * DIN;
;     Qg = Hb + C_SQ + hd * 64; qstr = DIN; kstr = vstr = 64;
;     Kg = (const u16*)(p.ws + OFF_SK) + (size_t)(b * 2 + hd / 3) * S * 64; Vg = (const u16*)(p.ws + OFF_SV) + (size_t)(b * 2 + hd / 3) * S * 64;
;     ocol = 640 + hd * 64;
;   }
;   float* brel = (float*)lds;
;   char* stage0 = lds + BREL_BYTES;
;   if (MODE != 0) {
;     const int bcol = MODE == 1 ? hd : 4 + hd;
;     for (int i = tid; i < 512; i += NTHR) {
;       int rel = i - 224, rc = rel < -128 ? -128 : (rel > 128 ? 128 : rel);
;       float bv = p.relb[t5_bucket(rc) * 10 + bcol] * LOG2E;
;       brel[i] = (MODE == 2 && rc != rel) ? -1e30f : bv;
;     }
;   }
;   bf16x8 qf[NMAP][QS];
;   {
;     const u16* qrow = Qg + (size_t)(q0w + l32) * qstr + hh * 8;
; #pragma unroll
;     for (int mp = 0; mp < NMAP; ++mp)
; #pragma unroll
;       for (int st = 0; st < QS; ++st) qf[mp][st] = *(const bf16x8*)(qrow + (mp * QS + st) * 16);
;   }
;   f32x16 O[NMAP][2]; float m = 0.f, l[NMAP];
; #pragma unroll
;   for (int mp = 0; mp < NMAP; ++mp) {
; #pragma unroll
;     for (int r = 0; r < 16; ++r) { O[mp][0][r] = 0.f; O[mp][1][r] = 0.f; }
;     l[mp] = 0.f;
;   }
;   if (MODE == 2) { m = p.sink[layer * 6 + hd] * LOG2E; l[0] = (hh == 0) ? 1.f : 0.f; }
;   int kt0 = 0, kt1 = S / 64;
;   if (MODE == 2) { kt0 = (q0 - 128) / 64; if (kt0 < 0) kt0 = 0; kt1 = (q0 + 384) / 64; if (kt1 > S / 64) kt1 = S / 64; }
;   const int nt = kt1 - kt0;
;   constexpr int KSTRG = MODE == 0 ? 96 : 64, VSTRG = 64;
.LBB0_403:
	s_ashr_i32 s5, s60, 5
	s_and_b32 s4, s60, 7
	s_and_b32 s5, s5, -8
	v_mov_b32_e32 v14, v184
	s_or_b32 s4, s5, s4
	s_lshl_b32 s5, s60, 5
	s_waitcnt vmcnt(0)
	v_ashrrev_i32_e32 v0, 1, v14
	s_and_b32 s5, s5, 0x1f00
	v_and_b32_e32 v0, 0xffffffe0, v0
	v_add_u32_e32 v186, s5, v0
	s_mul_hi_i32 s5, s4, 0x2aaaaaab
	s_lshr_b32 s6, s5, 31
	s_add_i32 s10, s5, s6
	s_mul_i32 s5, s10, 6
	s_sub_i32 s52, s4, s5
	s_mul_i32 s6, s10, 0x900000
	v_readlane_b32 s8, v254, 45
	s_mul_hi_i32 s5, s10, 0x900000
	v_readlane_b32 s9, v254, 46
	s_add_u32 s8, s8, s6
	s_mul_i32 s6, s52, 0x60
	s_addc_u32 s5, s9, s5
	s_ashr_i32 s7, s6, 31
	s_lshl_b64 s[6:7], s[6:7], 1
	s_add_u32 s6, s8, s6
	v_and_b32_e32 v204, 31, v14
	s_addc_u32 s7, s5, s7
	v_bfe_u32 v15, v14, 5, 1
	v_or_b32_e32 v2, v186, v204
	v_mov_b64_e32 v[0:1], s[6:7]
	s_movk_i32 s5, 0x480
	v_mad_i64_i32 v[0:1], s[6:7], v2, s5, v[0:1]
	v_lshlrev_b32_e32 v16, 4, v15
	v_mov_b32_e32 v17, v5
	v_lshl_add_u64 v[0:1], v[0:1], 0, v[16:17]
	global_load_dwordx4 v[104:107], v[0:1], off
	global_load_dwordx4 v[108:111], v[0:1], off offset:32
	global_load_dwordx4 v[112:115], v[0:1], off offset:64
	global_load_dwordx4 v[116:119], v[0:1], off offset:96
	global_load_dwordx4 v[120:123], v[0:1], off offset:128
	global_load_dwordx4 v[124:127], v[0:1], off offset:160
	s_ashr_i32 s5, s4, 31
	s_mul_hi_i32 s6, s4, 0x180000
	s_mul_i32 s7, s4, 0x180000
	s_lshl_b64 s[4:5], s[4:5], 20
	s_add_u32 s12, s68, s4
	s_addc_u32 s11, s69, s5
	s_add_u32 s20, s66, s7
	s_addc_u32 s4, s67, s6
	s_and_b32 s21, s4, 0xffff
	s_movk_i32 s4, 0x300
	v_cmp_gt_i32_e64 s[4:5], s4, v14
	v_lshlrev_b32_e32 v187, 4, v14
	v_mov_b32_e32 v100, 0
	v_mov_b32_e32 v96, 0
	v_mov_b32_e32 v97, 0
	v_mov_b32_e32 v98, 0
	v_mov_b32_e32 v99, 0
	s_barrier
	s_and_b32 s13, s11, 0xffff
	s_ashr_i32 s11, s10, 31
	s_mov_b32 s23, s15
	v_bfe_u32 v206, v184, 5, 1
	v_lshlrev_b32_e32 v206, 2, v206
	v_and_b32_e32 v196, 31, v184
	v_bfe_u32 v197, v184, 5, 1
	v_mov_b32_e32 v199, 208
	v_mul_u32_u24_e32 v200, v196, v199
	v_lshl_add_u32 v200, v197, 4, v200
	v_bfe_u32 v199, v184, 2, 2
	v_lshl_add_u32 v199, v197, 2, v199
	v_mov_b32_e32 v208, 192
	v_mul_u32_u24_e32 v201, v199, v208
	v_bfe_u32 v199, v184, 4, 1
	v_lshl_add_u32 v201, v199, 5, v201
	v_and_b32_e32 v199, 3, v184
	v_lshl_add_u32 v201, v199, 3, v201
	v_mov_b32_e32 v208, 0xaaab
	v_mul_u32_u24_e32 v196, v184, v208
	v_lshrrev_b32_e32 v196, 19, v196
	v_mul_u32_u24_e32 v197, 12, v196
	v_sub_u32_e32 v197, v184, v197
	v_mov_b32_e32 v199, 208
	v_mul_u32_u24_e32 v202, v196, v199
	v_lshl_add_u32 v202, v197, 4, v202
	v_lshrrev_b32_e32 v196, 1, v184
	v_add_u32_e32 v196, 0x200, v196
	v_mul_u32_u24_e32 v197, v196, v208
	v_lshrrev_b32_e32 v197, 19, v197
	v_mul_u32_u24_e32 v209, 12, v197
	v_sub_u32_e32 v196, v196, v209
	v_mul_u32_u24_e32 v203, v197, v199
	v_lshl_add_u32 v203, v196, 4, v203
	v_and_b32_e32 v196, 1, v184
	v_lshl_add_u32 v203, v196, 3, v203
	v_lshrrev_b32_e32 v196, 3, v184
	v_mov_b32_e32 v199, 192
	v_mul_u32_u24_e32 v207, v196, v199
	v_and_b32_e32 v196, 7, v184
	v_lshl_add_u32 v207, v196, 4, v207
	v_lshlrev_b32_e32 v187, 4, v184
	v_lshlrev_b32_e32 v205, 3, v184
	v_add_u32_e32 v205, 0x2000, v205
	v_bfe_u32 v197, v184, 5, 1
	v_cmp_eq_u32_e64 s[8:9], 0, v197
	v_mov_b32_e32 v196, 0x3f803f80
	s_nop 0
	v_cndmask_b32_e64 v240, 0, v196, s[8:9]
	v_mov_b32_e32 v241, 0
	v_mov_b32_e32 v245, 0
	v_mov_b32_e32 v242, 0
	v_mov_b32_e32 v246, 0
	v_mov_b32_e32 v243, 0
	v_mov_b32_e32 v247, 0
	buffer_load_dwordx4 v[64:67], v187, s[20:23], 0 offen
	buffer_load_dwordx2 v[68:69], v205, s[20:23], 0 offen
	buffer_load_dwordx4 v[72:75], v187, s[12:15], 0 offen
	s_movk_i32 s62, 0x3000
	buffer_load_dwordx4 v[76:79], v187, s[20:23], s62 offen
	buffer_load_dwordx2 v[80:81], v205, s[20:23], s62 offen
	s_waitcnt vmcnt(0)
	ds_write_b128 v202, v[64:67] offset:2048
	ds_write_b64 v203, v[68:69] offset:2048
	ds_write_b128 v207, v[72:75] offset:15360
	ds_write_b128 v202, v[76:79] offset:27648
	ds_write_b64 v203, v[80:81] offset:27648
	s_movk_i32 s62, 0x6000
	s_movk_i32 s29, 0x2000
	buffer_load_dwordx4 v[96:99], v187, s[20:23], s62 offen
	buffer_load_dwordx2 v[100:101], v205, s[20:23], s62 offen
	buffer_load_dwordx4 v[188:191], v187, s[12:15], s29 offen
	s_mov_b32 s62, 0x9000
	s_movk_i32 s29, 0x4000
	buffer_load_dwordx4 v[230:233], v187, s[20:23], s62 offen
	buffer_load_dwordx2 v[234:235], v205, s[20:23], s62 offen
	buffer_load_dwordx4 v[236:239], v187, s[12:15], s29 offen
	s_mov_b32 s62, 0xc000
	s_movk_i32 s29, 0x6000
	s_waitcnt lgkmcnt(0)
	s_barrier
; #define MFMA(a, b, c) __builtin_amdgcn_mfma_f32_32x32x16_bf16((a), (b), (c), 0, 0, 0)
; template <int MODE>
; DI void attn_item(const Params& p, int layer, int bh, int qb, char* lds) {
;     ...
;         for (int sub = 0; sub < 2; ++sub) {
; #pragma unroll
;           for (int st = 0; st < QS; ++st) {
;             bf16x8 kf = *(const bf16x8*)(Ks + (32 * sub + l32) * KSTR + ((mp * QS + st) * 16 + hh * 8) * 2);
;             if (st == 0) s[sub] = MFMA(kf, qf[mp][st], c0tile); else s[sub] = MFMA(kf, qf[mp][st], s[sub]);
;           }
;         }
;         __builtin_amdgcn_iglp_opt(1);
;         __builtin_amdgcn_s_setprio(0);
;         if (NMAP == 1) {
;           lds_s16x4* vb = (lds_s16x4*)(Ks + KBYTES + vlane);
; #pragma unroll
;           for (int i = 0; i < 16; ++i) {
;             const int sub_ = i >> 3, ks_ = (i >> 2) & 1, dt_ = (i >> 1) & 1, g_ = i & 1;
;             vpre[i] = __builtin_amdgcn_ds_read_tr16_b64_v4i16(vb + ((32 * sub_ + 16 * ks_ + 8 * g_) * VSTR + 64 * dt_) / 8);
;           }
;           __builtin_amdgcn_sched_barrier(0);
;         }
;         if (MODE != 0 && !far) {
; #pragma unroll
;           for (int sub = 0; sub < 2; ++sub)
; #pragma unroll
;             for (int r = 0; r < 16; ++r) s[sub][r] += brow[32 * sub + (r & 3) + 8 * (r >> 2)];
;         }
;         const bool first = (MODE != 2) && (t == 0) && (mp == 0);
;         auto rebase = [&]() {
;           float mx = fmaxf(fmaxf(s[0][0], s[0][1]), s[0][2]);
; #pragma unroll
;           for (int r = 3; r < 15; r += 2) mx = fmaxf(fmaxf(mx, s[0][r]), s[0][r + 1]);
;           mx = fmaxf(mx, s[0][15]);
; #pragma unroll
;           for (int r = 0; r < 16; r += 2) mx = fmaxf(fmaxf(mx, s[1][r]), s[1][r + 1]);
;           const float rm = xchg_max(mx);
;           float delta = first ? rm : fmaxf(rm, 0.f);
;           if (delta < -1e29f) delta = 0.f;
;           m += delta;
;           const float alpha = __builtin_amdgcn_exp2f(-delta);
; #pragma unroll
;           for (int mq = 0; mq < NMAP; ++mq) {
;             l[mq] *= alpha;
; #pragma unroll
;             for (int r = 0; r < 16; ++r) { O[mq][0][r] *= alpha; O[mq][1][r] *= alpha; }
;           }
; #pragma unroll
;           for (int r = 0; r < 16; ++r) { s[0][r] -= delta; s[1][r] -= delta; }
;           set_c0(cb - m);
	ds_read_b128 v[176:179], v200 offset:2048
	ds_read_b128 v[180:183], v200 offset:2080
	ds_read_b128 v[222:225], v200 offset:2112
	s_waitcnt lgkmcnt(2)
	v_mfma_f32_32x32x16_bf16 v[64:79], v[176:179], v[104:107], 0
	ds_read_b128 v[226:229], v200 offset:2144
	s_waitcnt lgkmcnt(2)
	v_mfma_f32_32x32x16_bf16 v[64:79], v[180:183], v[108:111], v[64:79]
	ds_read_b128 v[176:179], v200 offset:2176
	s_waitcnt lgkmcnt(2)
	v_mfma_f32_32x32x16_bf16 v[64:79], v[222:225], v[112:115], v[64:79]
	ds_read_b128 v[180:183], v200 offset:2208
	s_waitcnt lgkmcnt(2)
	v_mfma_f32_32x32x16_bf16 v[64:79], v[226:229], v[116:119], v[64:79]
	ds_read_b128 v[222:225], v200 offset:8704
	s_waitcnt lgkmcnt(2)
	v_mfma_f32_32x32x16_bf16 v[64:79], v[176:179], v[120:123], v[64:79]
	ds_read_b128 v[226:229], v200 offset:8736
	s_waitcnt lgkmcnt(2)
	v_mfma_f32_32x32x16_bf16 v[64:79], v[180:183], v[124:127], v[64:79]
	ds_read_b128 v[176:179], v200 offset:8768
	s_waitcnt lgkmcnt(2)
	v_mfma_f32_32x32x16_bf16 v[80:95], v[222:225], v[104:107], 0
	ds_read_b128 v[180:183], v200 offset:8800
	s_waitcnt lgkmcnt(2)
	v_mfma_f32_32x32x16_bf16 v[80:95], v[226:229], v[108:111], v[80:95]
	ds_read_b128 v[222:225], v200 offset:8832
	s_waitcnt lgkmcnt(2)
	v_mfma_f32_32x32x16_bf16 v[80:95], v[176:179], v[112:115], v[80:95]
	ds_read_b128 v[226:229], v200 offset:8864
	s_waitcnt lgkmcnt(2)
	v_mfma_f32_32x32x16_bf16 v[80:95], v[180:183], v[116:119], v[80:95]
	s_waitcnt lgkmcnt(1)
	v_mfma_f32_32x32x16_bf16 v[80:95], v[222:225], v[120:123], v[80:95]
	s_waitcnt lgkmcnt(0)
	v_mfma_f32_32x32x16_bf16 v[80:95], v[226:229], v[124:127], v[80:95]
	v_mov_b32_e32 v16, 0
	v_mov_b32_e32 v32, 0
	v_mov_b32_e32 v17, 0
	v_mov_b32_e32 v33, 0
	v_mov_b32_e32 v18, 0
	v_mov_b32_e32 v34, 0
	v_mov_b32_e32 v19, 0
	v_mov_b32_e32 v35, 0
	v_mov_b32_e32 v20, 0
	v_mov_b32_e32 v36, 0
	v_mov_b32_e32 v21, 0
	v_mov_b32_e32 v37, 0
	v_mov_b32_e32 v22, 0
	v_mov_b32_e32 v38, 0
	v_mov_b32_e32 v23, 0
	v_mov_b32_e32 v39, 0
	v_mov_b32_e32 v24, 0
	v_mov_b32_e32 v40, 0
	v_mov_b32_e32 v25, 0
	v_mov_b32_e32 v41, 0
	v_mov_b32_e32 v26, 0
	v_mov_b32_e32 v42, 0
	v_mov_b32_e32 v27, 0
	v_mov_b32_e32 v43, 0
	v_mov_b32_e32 v28, 0
	v_mov_b32_e32 v44, 0
	v_mov_b32_e32 v29, 0
	v_mov_b32_e32 v45, 0
	v_mov_b32_e32 v30, 0
	v_mov_b32_e32 v46, 0
	v_mov_b32_e32 v31, 0
	v_mov_b32_e32 v47, 0
	v_mov_b32_e32 v192, 0
	v_mov_b32_e32 v193, 0
	s_waitcnt lgkmcnt(0)
	s_barrier
	v_max_f32_e32 v196, v64, v65
	v_max3_f32 v196, v196, v66, v67
	v_max3_f32 v196, v196, v68, v69
	v_max3_f32 v196, v196, v70, v71
	v_max3_f32 v196, v196, v72, v73
	v_max3_f32 v196, v196, v74, v75
	v_max3_f32 v196, v196, v76, v77
	v_max3_f32 v196, v196, v78, v79
	v_max3_f32 v196, v196, v80, v81
	v_max3_f32 v196, v196, v82, v83
	v_max3_f32 v196, v196, v84, v85
	v_max3_f32 v196, v196, v86, v87
	v_max3_f32 v196, v196, v88, v89
	v_max3_f32 v196, v196, v90, v91
	v_max3_f32 v196, v196, v92, v93
	v_max3_f32 v196, v196, v94, v95
	v_mov_b32_e32 v197, v196
	s_nop 1
	v_permlane32_swap_b32_e32 v196, v197
	v_max_f32_e32 v196, v196, v197
	s_mov_b32 s24, 0xefa18f08
	v_cmp_ngt_f32_e32 vcc, s24, v196
	s_nop 1
	v_cndmask_b32_e32 v198, 0, v196, vcc
	v_sub_f32_e32 v64, v64, v198
	v_sub_f32_e32 v65, v65, v198
	v_sub_f32_e32 v66, v66, v198
	v_sub_f32_e32 v67, v67, v198
	v_sub_f32_e32 v68, v68, v198
	v_sub_f32_e32 v69, v69, v198
	v_sub_f32_e32 v70, v70, v198
	v_sub_f32_e32 v71, v71, v198
	v_sub_f32_e32 v72, v72, v198
	v_sub_f32_e32 v73, v73, v198
	v_sub_f32_e32 v74, v74, v198
	v_sub_f32_e32 v75, v75, v198
	v_sub_f32_e32 v76, v76, v198
	v_sub_f32_e32 v77, v77, v198
	v_sub_f32_e32 v78, v78, v198
	v_sub_f32_e32 v79, v79, v198
	v_sub_f32_e32 v80, v80, v198
	v_sub_f32_e32 v81, v81, v198
	v_sub_f32_e32 v82, v82, v198
	v_sub_f32_e32 v83, v83, v198
	v_sub_f32_e32 v84, v84, v198
	v_sub_f32_e32 v85, v85, v198
	v_sub_f32_e32 v86, v86, v198
	v_sub_f32_e32 v87, v87, v198
	v_sub_f32_e32 v88, v88, v198
	v_sub_f32_e32 v89, v89, v198
	v_sub_f32_e32 v90, v90, v198
	v_sub_f32_e32 v91, v91, v198
	v_sub_f32_e32 v92, v92, v198
	v_sub_f32_e32 v93, v93, v198
	v_sub_f32_e32 v94, v94, v198
	v_sub_f32_e32 v95, v95, v198
	v_sub_f32_e32 v196, 0, v198
	v_bfe_u32 v197, v196, 16, 1
	v_add3_u32 v196, v196, v197, s45
	v_lshrrev_b32_e32 v197, 16, v196
	v_and_b32_e32 v196, 0xffff0000, v196
	v_sub_f32_e64 v196, -v198, v196
	v_bfe_u32 v199, v196, 16, 1
	v_add3_u32 v196, v196, v199, s45
	v_and_or_b32 v196, v196, s92, v197
	v_cndmask_b32_e64 v244, 0, v196, s[8:9]
	s_nop 1
	v_mfma_f32_32x32x16_bf16 v[48:63], v[240:243], v[244:247], 0
	s_mov_b32 s28, 0
	v_readfirstlane_b32 s24, v184
	s_nop 3
	s_cmpk_ge_u32 s24, 0x100
	s_cbranch_scc0 .Lmla_prio
	s_setprio 1
; #define MFMA(a, b, c) __builtin_amdgcn_mfma_f32_32x32x16_bf16((a), (b), (c), 0, 0, 0)
; DI unsigned pk2(float lo, float hi) { f32x2 v = {lo, hi}; b16x2 r = __builtin_convertvector(v, b16x2); return __builtin_bit_cast(unsigned, r); }
; template <int MODE>
; DI void attn_item(const Params& p, int layer, int bh, int qb, char* lds) {
;     ...
; #pragma unroll
;           for (int st = 0; st < QS; ++st) {
;             bf16x8 kf = *(const bf16x8*)(Ks + (32 * sub + l32) * KSTR + ((mp * QS + st) * 16 + hh * 8) * 2);
;             if (st == 0) s[sub] = MFMA(kf, qf[mp][st], c0tile); else s[sub] = MFMA(kf, qf[mp][st], s[sub]);
;           }
;         }
;     ...
;         auto smpass = [&]() {
;           ps = 0.f;
; #pragma unroll
;           for (int sub = 0; sub < 2; ++sub)
; #pragma unroll
;             for (int ks = 0; ks < 2; ++ks)
; #pragma unroll
;               for (int i = 0; i < 4; ++i) {
;                 const float p0 = __builtin_amdgcn_exp2f(s[sub][8 * ks + 2 * i]), p1 = __builtin_amdgcn_exp2f(s[sub][8 * ks + 2 * i + 1]);
;                 ps += p0 + p1; pk[mp][sub][ks][i] = pk2(p0, p1);
;               }
;         };
;         if (first) rebase();
;         smpass();
;         if (!first && __any(!(ps <= PSLIM))) { rebase(); smpass(); }
;         l[mp] += ps;
;         __builtin_amdgcn_sched_barrier(0);
;       }
; #pragma unroll
;       for (int sub = 0; sub < 2; ++sub) {
;         s16x4 vv[8];
;         if (NMAP == 1) {
; #pragma unroll
;           for (int i = 0; i < 8; ++i) vv[i] = vpre[sub * 8 + i];
;         } else {
;           if (sub == 0) trread8<0>(vaddr, vv); else trread8<32 * VSTR>(vaddr, vv);
;         }
;         __builtin_amdgcn_s_setprio(1);
; #pragma unroll
;         for (int ks = 0; ks < 2; ++ks) {
; #pragma unroll
;           for (int dt = 0; dt < 2; ++dt) {
;             s16x4 lo = vv[ks * 4 + dt * 2], hi = vv[ks * 4 + dt * 2 + 1];
;             bf16x8 vf = __builtin_shufflevector(lo, hi, 0, 1, 2, 3, 4, 5, 6, 7);
; #pragma unroll
;             for (int mp = 0; mp < NMAP; ++mp) O[mp][dt] = MFMA(vf, __builtin_bit_cast(bf16x8, pk[mp][sub][ks]), O[mp][dt]);
;           }
;         }
;         __builtin_amdgcn_s_setprio(0);
;         __builtin_amdgcn_sched_barrier(0);
;       }
.Lmla_prio:
.Lmla_loop:
	ds_read_b128 v[176:179], v200 offset:27648
	ds_read_b128 v[180:183], v200 offset:27680
	ds_read_b128 v[222:225], v200 offset:27712
	s_waitcnt vmcnt(3)
	ds_write_b128 v202, v[96:99] offset:2048
	ds_write_b64 v203, v[100:101] offset:2048
	ds_write_b128 v207, v[188:191] offset:40960
	buffer_load_dwordx4 v[96:99], v187, s[20:23], s62 offen
	buffer_load_dwordx2 v[100:101], v205, s[20:23], s62 offen
	buffer_load_dwordx4 v[188:191], v187, s[12:15], s29 offen
	s_add_u32 s62, s62, 0x3000
	s_add_u32 s29, s29, 0x2000
	v_exp_f32_e32 v0, v64
	v_exp_f32_e32 v1, v65
	v_exp_f32_e32 v2, v66
	v_exp_f32_e32 v3, v67
	v_add_f32_e32 v10, v0, v1
	v_cvt_pk_bf16_f32 v160, v0, v1
	s_waitcnt lgkmcnt(5)
	v_mfma_f32_32x32x16_bf16 v[128:143], v[176:179], v[104:107], v[48:63]
	ds_read_b128 v[226:229], v200 offset:27744
	s_waitcnt lgkmcnt(5)
	v_mfma_f32_32x32x16_bf16 v[128:143], v[180:183], v[108:111], v[128:143]
	ds_read_b64_tr_b16 v[176:177], v201 offset:15360
	ds_read_b64_tr_b16 v[178:179], v201 offset:16896
	v_add_f32_e32 v10, v10, v2
	v_add_f32_e32 v10, v10, v3
	v_cvt_pk_bf16_f32 v161, v2, v3
	s_waitcnt lgkmcnt(6)
	v_mfma_f32_32x32x16_bf16 v[128:143], v[222:225], v[112:115], v[128:143]
	ds_read_b64_tr_b16 v[180:181], v201 offset:15424
	ds_read_b64_tr_b16 v[182:183], v201 offset:16960
	v_exp_f32_e32 v6, v68
	v_exp_f32_e32 v7, v69
	v_exp_f32_e32 v8, v70
	v_exp_f32_e32 v9, v71
	v_add_f32_e32 v10, v10, v6
	s_waitcnt lgkmcnt(4)
	v_mfma_f32_32x32x16_bf16 v[128:143], v[226:229], v[116:119], v[128:143]
	ds_read_b128 v[222:225], v200 offset:27776
	v_add_f32_e32 v10, v10, v7
	v_cvt_pk_bf16_f32 v162, v6, v7
	v_add_f32_e32 v10, v10, v8
	v_add_f32_e32 v10, v10, v9
	v_cvt_pk_bf16_f32 v163, v8, v9
	s_waitcnt lgkmcnt(3)
	s_nop 0
	v_mfma_f32_32x32x16_bf16 v[32:47], v[176:179], v[160:163], v[32:47]
	ds_read_b128 v[226:229], v200 offset:27808
	v_exp_f32_e32 v0, v72
	v_exp_f32_e32 v1, v73
	v_exp_f32_e32 v2, v74
	s_waitcnt lgkmcnt(2)
	v_mfma_f32_32x32x16_bf16 v[16:31], v[180:183], v[160:163], v[16:31]
	ds_read_b128 v[176:179], v200 offset:34304
	v_exp_f32_e32 v3, v75
	v_add_f32_e32 v11, v0, v1
	v_cvt_pk_bf16_f32 v164, v0, v1
	v_add_f32_e32 v11, v11, v2
	s_waitcnt lgkmcnt(2)
	v_mfma_f32_32x32x16_bf16 v[128:143], v[222:225], v[120:123], v[128:143]
	ds_read_b64_tr_b16 v[180:181], v201 offset:18432
	ds_read_b64_tr_b16 v[182:183], v201 offset:19968
	v_add_f32_e32 v11, v11, v3
	v_cvt_pk_bf16_f32 v165, v2, v3
	v_exp_f32_e32 v6, v76
	v_exp_f32_e32 v7, v77
	s_waitcnt lgkmcnt(3)
	v_mfma_f32_32x32x16_bf16 v[128:143], v[226:229], v[124:127], v[128:143]
	ds_read_b64_tr_b16 v[222:223], v201 offset:18496
	ds_read_b64_tr_b16 v[224:225], v201 offset:20032
	v_exp_f32_e32 v8, v78
	v_exp_f32_e32 v9, v79
	v_add_f32_e32 v11, v11, v6
	v_add_f32_e32 v11, v11, v7
	s_waitcnt lgkmcnt(4)
	v_mfma_f32_32x32x16_bf16 v[144:159], v[176:179], v[104:107], v[48:63]
	ds_read_b128 v[226:229], v200 offset:34336
	v_cvt_pk_bf16_f32 v166, v6, v7
	v_add_f32_e32 v11, v11, v8
	v_add_f32_e32 v11, v11, v9
	v_cvt_pk_bf16_f32 v167, v8, v9
	s_waitcnt lgkmcnt(3)
	s_nop 0
	v_mfma_f32_32x32x16_bf16 v[32:47], v[180:183], v[164:167], v[32:47]
	ds_read_b128 v[176:179], v200 offset:34368
	v_exp_f32_e32 v0, v80
	v_exp_f32_e32 v1, v81
	v_exp_f32_e32 v2, v82
	s_waitcnt lgkmcnt(2)
	v_mfma_f32_32x32x16_bf16 v[16:31], v[222:225], v[164:167], v[16:31]
	ds_read_b128 v[180:183], v200 offset:34400
	v_exp_f32_e32 v3, v83
	v_add_f32_e32 v12, v0, v1
	v_cvt_pk_bf16_f32 v168, v0, v1
	v_add_f32_e32 v12, v12, v2
	s_waitcnt lgkmcnt(2)
	v_mfma_f32_32x32x16_bf16 v[144:159], v[226:229], v[108:111], v[144:159]
	ds_read_b64_tr_b16 v[222:223], v201 offset:21504
	ds_read_b64_tr_b16 v[224:225], v201 offset:23040
	v_add_f32_e32 v12, v12, v3
	v_cvt_pk_bf16_f32 v169, v2, v3
	v_exp_f32_e32 v6, v84
	v_exp_f32_e32 v7, v85
	s_waitcnt lgkmcnt(3)
	v_mfma_f32_32x32x16_bf16 v[144:159], v[176:179], v[112:115], v[144:159]
	ds_read_b64_tr_b16 v[226:227], v201 offset:21568
	ds_read_b64_tr_b16 v[228:229], v201 offset:23104
	v_exp_f32_e32 v8, v86
	v_exp_f32_e32 v9, v87
	v_add_f32_e32 v12, v12, v6
	v_add_f32_e32 v12, v12, v7
	s_waitcnt lgkmcnt(4)
	v_mfma_f32_32x32x16_bf16 v[144:159], v[180:183], v[116:119], v[144:159]
	ds_read_b128 v[176:179], v200 offset:34432
	v_cvt_pk_bf16_f32 v170, v6, v7
	v_add_f32_e32 v12, v12, v8
	v_add_f32_e32 v12, v12, v9
	v_cvt_pk_bf16_f32 v171, v8, v9
	s_waitcnt lgkmcnt(3)
	s_nop 0
	v_mfma_f32_32x32x16_bf16 v[32:47], v[222:225], v[168:171], v[32:47]
	ds_read_b128 v[180:183], v200 offset:34464
	v_exp_f32_e32 v0, v88
	v_exp_f32_e32 v1, v89
	v_exp_f32_e32 v2, v90
	v_exp_f32_e32 v3, v91
	s_waitcnt lgkmcnt(2)
	v_mfma_f32_32x32x16_bf16 v[16:31], v[226:229], v[168:171], v[16:31]
	ds_read_b64_tr_b16 v[222:223], v201 offset:24576
	ds_read_b64_tr_b16 v[224:225], v201 offset:26112
	v_add_f32_e32 v13, v0, v1
	v_cvt_pk_bf16_f32 v172, v0, v1
	v_add_f32_e32 v13, v13, v2
	v_add_f32_e32 v13, v13, v3
	v_cvt_pk_bf16_f32 v173, v2, v3
	s_waitcnt lgkmcnt(3)
	v_mfma_f32_32x32x16_bf16 v[144:159], v[176:179], v[120:123], v[144:159]
	ds_read_b64_tr_b16 v[226:227], v201 offset:24640
	ds_read_b64_tr_b16 v[228:229], v201 offset:26176
	v_exp_f32_e32 v6, v92
	v_exp_f32_e32 v7, v93
	v_exp_f32_e32 v8, v94
	v_exp_f32_e32 v9, v95
	v_add_f32_e32 v13, v13, v6
	s_waitcnt lgkmcnt(4)
	v_mfma_f32_32x32x16_bf16 v[144:159], v[180:183], v[124:127], v[144:159]
	v_add_f32_e32 v13, v13, v7
	v_cvt_pk_bf16_f32 v174, v6, v7
	v_add_f32_e32 v13, v13, v8
	v_add_f32_e32 v13, v13, v9
	v_cvt_pk_bf16_f32 v175, v8, v9
	s_waitcnt lgkmcnt(2)
	s_nop 0
	v_mfma_f32_32x32x16_bf16 v[32:47], v[222:225], v[172:175], v[32:47]
	s_waitcnt lgkmcnt(0)
	v_mfma_f32_32x32x16_bf16 v[16:31], v[226:229], v[172:175], v[16:31]
	v_add_f32_e32 v10, v10, v11
	v_add_f32_e32 v12, v12, v13
	v_add_f32_e32 v10, v10, v12
	v_add_f32_e32 v192, v192, v10
	v_max_f32_e32 v193, v193, v10
	s_waitcnt lgkmcnt(0)
	s_barrier
; #define MFMA(a, b, c) __builtin_amdgcn_mfma_f32_32x32x16_bf16((a), (b), (c), 0, 0, 0)
; DI unsigned pk2(float lo, float hi) { f32x2 v = {lo, hi}; b16x2 r = __builtin_convertvector(v, b16x2); return __builtin_bit_cast(unsigned, r); }
; template <int MODE>
; DI void attn_item(const Params& p, int layer, int bh, int qb, char* lds) {
;     ...
; #pragma unroll
;           for (int st = 0; st < QS; ++st) {
;             bf16x8 kf = *(const bf16x8*)(Ks + (32 * sub + l32) * KSTR + ((mp * QS + st) * 16 + hh * 8) * 2);
;             if (st == 0) s[sub] = MFMA(kf, qf[mp][st], c0tile); else s[sub] = MFMA(kf, qf[mp][st], s[sub]);
;           }
;         }
;     ...
;         auto smpass = [&]() {
;           ps = 0.f;
; #pragma unroll
;           for (int sub = 0; sub < 2; ++sub)
; #pragma unroll
;             for (int ks = 0; ks < 2; ++ks)
; #pragma unroll
;               for (int i = 0; i < 4; ++i) {
;                 const float p0 = __builtin_amdgcn_exp2f(s[sub][8 * ks + 2 * i]), p1 = __builtin_amdgcn_exp2f(s[sub][8 * ks + 2 * i + 1]);
;                 ps += p0 + p1; pk[mp][sub][ks][i] = pk2(p0, p1);
;               }
;         };
;         if (first) rebase();
;         smpass();
;         if (!first && __any(!(ps <= PSLIM))) { rebase(); smpass(); }
;         l[mp] += ps;
;         __builtin_amdgcn_sched_barrier(0);
;       }
; #pragma unroll
;       for (int sub = 0; sub < 2; ++sub) {
;         s16x4 vv[8];
;         if (NMAP == 1) {
; #pragma unroll
;           for (int i = 0; i < 8; ++i) vv[i] = vpre[sub * 8 + i];
;         } else {
;           if (sub == 0) trread8<0>(vaddr, vv); else trread8<32 * VSTR>(vaddr, vv);
;         }
;         __builtin_amdgcn_s_setprio(1);
; #pragma unroll
;         for (int ks = 0; ks < 2; ++ks) {
; #pragma unroll
;           for (int dt = 0; dt < 2; ++dt) {
;             s16x4 lo = vv[ks * 4 + dt * 2], hi = vv[ks * 4 + dt * 2 + 1];
;             bf16x8 vf = __builtin_shufflevector(lo, hi, 0, 1, 2, 3, 4, 5, 6, 7);
; #pragma unroll
;             for (int mp = 0; mp < NMAP; ++mp) O[mp][dt] = MFMA(vf, __builtin_bit_cast(bf16x8, pk[mp][sub][ks]), O[mp][dt]);
;           }
;         }
;         __builtin_amdgcn_s_setprio(0);
;         __builtin_amdgcn_sched_barrier(0);
;       }
	ds_read_b128 v[176:179], v200 offset:2048
	ds_read_b128 v[180:183], v200 offset:2080
	ds_read_b128 v[222:225], v200 offset:2112
	s_waitcnt vmcnt(3)
	ds_write_b128 v202, v[230:233] offset:27648
	ds_write_b64 v203, v[234:235] offset:27648
	ds_write_b128 v207, v[236:239] offset:15360
	buffer_load_dwordx4 v[230:233], v187, s[20:23], s62 offen
	buffer_load_dwordx2 v[234:235], v205, s[20:23], s62 offen
	buffer_load_dwordx4 v[236:239], v187, s[12:15], s29 offen
	s_add_u32 s62, s62, 0x3000
	s_add_u32 s29, s29, 0x2000
	v_exp_f32_e32 v0, v128
	v_exp_f32_e32 v1, v129
	v_exp_f32_e32 v2, v130
	v_exp_f32_e32 v3, v131
	v_add_f32_e32 v10, v0, v1
	v_cvt_pk_bf16_f32 v160, v0, v1
	s_waitcnt lgkmcnt(5)
	v_mfma_f32_32x32x16_bf16 v[64:79], v[176:179], v[104:107], v[48:63]
	ds_read_b128 v[226:229], v200 offset:2144
	s_waitcnt lgkmcnt(5)
	v_mfma_f32_32x32x16_bf16 v[64:79], v[180:183], v[108:111], v[64:79]
	ds_read_b64_tr_b16 v[176:177], v201 offset:40960
	ds_read_b64_tr_b16 v[178:179], v201 offset:42496
	v_add_f32_e32 v10, v10, v2
	v_add_f32_e32 v10, v10, v3
	v_cvt_pk_bf16_f32 v161, v2, v3
	s_waitcnt lgkmcnt(6)
	v_mfma_f32_32x32x16_bf16 v[64:79], v[222:225], v[112:115], v[64:79]
	ds_read_b64_tr_b16 v[180:181], v201 offset:41024
	ds_read_b64_tr_b16 v[182:183], v201 offset:42560
	v_exp_f32_e32 v6, v132
	v_exp_f32_e32 v7, v133
	v_exp_f32_e32 v8, v134
	v_exp_f32_e32 v9, v135
	v_add_f32_e32 v10, v10, v6
	s_waitcnt lgkmcnt(4)
	v_mfma_f32_32x32x16_bf16 v[64:79], v[226:229], v[116:119], v[64:79]
	ds_read_b128 v[222:225], v200 offset:2176
	v_add_f32_e32 v10, v10, v7
	v_cvt_pk_bf16_f32 v162, v6, v7
	v_add_f32_e32 v10, v10, v8
	v_add_f32_e32 v10, v10, v9
	v_cvt_pk_bf16_f32 v163, v8, v9
	s_waitcnt lgkmcnt(3)
	s_nop 0
	v_mfma_f32_32x32x16_bf16 v[32:47], v[176:179], v[160:163], v[32:47]
	ds_read_b128 v[226:229], v200 offset:2208
	v_exp_f32_e32 v0, v136
	v_exp_f32_e32 v1, v137
	v_exp_f32_e32 v2, v138
	s_waitcnt lgkmcnt(2)
	v_mfma_f32_32x32x16_bf16 v[16:31], v[180:183], v[160:163], v[16:31]
	ds_read_b128 v[176:179], v200 offset:8704
	v_exp_f32_e32 v3, v139
	v_add_f32_e32 v11, v0, v1
	v_cvt_pk_bf16_f32 v164, v0, v1
	v_add_f32_e32 v11, v11, v2
	s_waitcnt lgkmcnt(2)
	v_mfma_f32_32x32x16_bf16 v[64:79], v[222:225], v[120:123], v[64:79]
	ds_read_b64_tr_b16 v[180:181], v201 offset:44032
	ds_read_b64_tr_b16 v[182:183], v201 offset:45568
	v_add_f32_e32 v11, v11, v3
	v_cvt_pk_bf16_f32 v165, v2, v3
	v_exp_f32_e32 v6, v140
	v_exp_f32_e32 v7, v141
	s_waitcnt lgkmcnt(3)
	v_mfma_f32_32x32x16_bf16 v[64:79], v[226:229], v[124:127], v[64:79]
	ds_read_b64_tr_b16 v[222:223], v201 offset:44096
	ds_read_b64_tr_b16 v[224:225], v201 offset:45632
	v_exp_f32_e32 v8, v142
	v_exp_f32_e32 v9, v143
	v_add_f32_e32 v11, v11, v6
	v_add_f32_e32 v11, v11, v7
	s_waitcnt lgkmcnt(4)
	v_mfma_f32_32x32x16_bf16 v[80:95], v[176:179], v[104:107], v[48:63]
	ds_read_b128 v[226:229], v200 offset:8736
	v_cvt_pk_bf16_f32 v166, v6, v7
	v_add_f32_e32 v11, v11, v8
	v_add_f32_e32 v11, v11, v9
	v_cvt_pk_bf16_f32 v167, v8, v9
	s_waitcnt lgkmcnt(3)
	s_nop 0
	v_mfma_f32_32x32x16_bf16 v[32:47], v[180:183], v[164:167], v[32:47]
	ds_read_b128 v[176:179], v200 offset:8768
	v_exp_f32_e32 v0, v144
	v_exp_f32_e32 v1, v145
	v_exp_f32_e32 v2, v146
	s_waitcnt lgkmcnt(2)
	v_mfma_f32_32x32x16_bf16 v[16:31], v[222:225], v[164:167], v[16:31]
	ds_read_b128 v[180:183], v200 offset:8800
	v_exp_f32_e32 v3, v147
	v_add_f32_e32 v12, v0, v1
	v_cvt_pk_bf16_f32 v168, v0, v1
	v_add_f32_e32 v12, v12, v2
	s_waitcnt lgkmcnt(2)
	v_mfma_f32_32x32x16_bf16 v[80:95], v[226:229], v[108:111], v[80:95]
	ds_read_b64_tr_b16 v[222:223], v201 offset:47104
	ds_read_b64_tr_b16 v[224:225], v201 offset:48640
	v_add_f32_e32 v12, v12, v3
	v_cvt_pk_bf16_f32 v169, v2, v3
	v_exp_f32_e32 v6, v148
	v_exp_f32_e32 v7, v149
	s_waitcnt lgkmcnt(3)
	v_mfma_f32_32x32x16_bf16 v[80:95], v[176:179], v[112:115], v[80:95]
	ds_read_b64_tr_b16 v[226:227], v201 offset:47168
	ds_read_b64_tr_b16 v[228:229], v201 offset:48704
	v_exp_f32_e32 v8, v150
	v_exp_f32_e32 v9, v151
	v_add_f32_e32 v12, v12, v6
	v_add_f32_e32 v12, v12, v7
	s_waitcnt lgkmcnt(4)
	v_mfma_f32_32x32x16_bf16 v[80:95], v[180:183], v[116:119], v[80:95]
	ds_read_b128 v[176:179], v200 offset:8832
	v_cvt_pk_bf16_f32 v170, v6, v7
	v_add_f32_e32 v12, v12, v8
	v_add_f32_e32 v12, v12, v9
	v_cvt_pk_bf16_f32 v171, v8, v9
	s_waitcnt lgkmcnt(3)
	s_nop 0
	v_mfma_f32_32x32x16_bf16 v[32:47], v[222:225], v[168:171], v[32:47]
	ds_read_b128 v[180:183], v200 offset:8864
	v_exp_f32_e32 v0, v152
	v_exp_f32_e32 v1, v153
	v_exp_f32_e32 v2, v154
	v_exp_f32_e32 v3, v155
	s_waitcnt lgkmcnt(2)
	v_mfma_f32_32x32x16_bf16 v[16:31], v[226:229], v[168:171], v[16:31]
	ds_read_b64_tr_b16 v[222:223], v201 offset:50176
	ds_read_b64_tr_b16 v[224:225], v201 offset:51712
	v_add_f32_e32 v13, v0, v1
	v_cvt_pk_bf16_f32 v172, v0, v1
	v_add_f32_e32 v13, v13, v2
	v_add_f32_e32 v13, v13, v3
	v_cvt_pk_bf16_f32 v173, v2, v3
	s_waitcnt lgkmcnt(3)
	v_mfma_f32_32x32x16_bf16 v[80:95], v[176:179], v[120:123], v[80:95]
	ds_read_b64_tr_b16 v[226:227], v201 offset:50240
	ds_read_b64_tr_b16 v[228:229], v201 offset:51776
	v_exp_f32_e32 v6, v156
	v_exp_f32_e32 v7, v157
	v_exp_f32_e32 v8, v158
	v_exp_f32_e32 v9, v159
	v_add_f32_e32 v13, v13, v6
	s_waitcnt lgkmcnt(4)
	v_mfma_f32_32x32x16_bf16 v[80:95], v[180:183], v[124:127], v[80:95]
	v_add_f32_e32 v13, v13, v7
	v_cvt_pk_bf16_f32 v174, v6, v7
	v_add_f32_e32 v13, v13, v8
	v_add_f32_e32 v13, v13, v9
	v_cvt_pk_bf16_f32 v175, v8, v9
	s_waitcnt lgkmcnt(2)
	s_nop 0
	v_mfma_f32_32x32x16_bf16 v[32:47], v[222:225], v[172:175], v[32:47]
	s_waitcnt lgkmcnt(0)
	v_mfma_f32_32x32x16_bf16 v[16:31], v[226:229], v[172:175], v[16:31]
	v_add_f32_e32 v10, v10, v11
	v_add_f32_e32 v12, v12, v13
	v_add_f32_e32 v10, v10, v12
	v_add_f32_e32 v192, v192, v10
	v_max_f32_e32 v193, v193, v10
	s_add_u32 s28, s28, 2
	s_cmpk_lt_u32 s28, 0x80
	s_waitcnt lgkmcnt(0)
	s_barrier
; DI unsigned pk2(float lo, float hi) { f32x2 v = {lo, hi}; b16x2 r = __builtin_convertvector(v, b16x2); return __builtin_bit_cast(unsigned, r); }
; DI float bflo(unsigned w) { return __uint_as_float(w << 16); }
; DI float bfhi(unsigned w) { return __uint_as_float(w & 0xffff0000u); }
; template <int MODE>
; DI void attn_item(const Params& p, int layer, int bh, int qb, char* lds) {
;     ...
;   __syncthreads();
;   const size_t trow = (size_t)b * S + q0w + l32;
;   const u16* grow = (const u16*)(p.ws + OFF_H) + trow * DIN + C_GATE + ocol;
;   u16* orow = (u16*)(p.ws + OFF_OB) + trow * DM + ocol;
;   float inv0 = 1.f / xchg_sum(l[0]);
;   if (MODE == 1) {
;     const float* lm = (const float*)(p.ws + OFF_LAM);
;     const float lam = lm[layer], post = lm[4 + layer];
;     const float inv1 = lam / xchg_sum(l[1]);
;     float ss = 0.f;
; #pragma unroll
;     for (int dt = 0; dt < 2; ++dt)
; #pragma unroll
;       for (int r = 0; r < 16; ++r) { float v = O[0][dt][r] * inv0 - O[NMAP - 1][dt][r] * inv1; O[0][dt][r] = v; ss += v * v; }
;     ss = xchg_sum(ss);
;     inv0 = rsqrtf(ss * (1.f / 64.f) + 1e-6f) * post;
;   }
; #pragma unroll
;   for (int dt = 0; dt < 2; ++dt)
; #pragma unroll
;     for (int g = 0; g < 4; ++g) {
;       const int d = 32 * dt + 8 * g + 4 * hh;
;       u32x2 gw = *(const u32x2*)(grow + d);
;       float v0 = O[0][dt][4 * g + 0] * inv0, v1 = O[0][dt][4 * g + 1] * inv0, v2 = O[0][dt][4 * g + 2] * inv0, v3 = O[0][dt][4 * g + 3] * inv0;
;       if (MODE == 1) { const float* sl = p.subln + layer * 64 + d; v0 *= sl[0]; v1 *= sl[1]; v2 *= sl[2]; v3 *= sl[3]; }
;       v0 *= bflo(gw[0]); v1 *= bfhi(gw[0]); v2 *= bflo(gw[1]); v3 *= bfhi(gw[1]);
;       u32x2 ow = {pk2(v0, v1), pk2(v2, v3)};
;     ...
;       if (MODE == PROBE_ZERO_MODE) { ow[0] = 0u; ow[1] = 0u; }
;     ...
;       *(u32x2*)(orow + d) = ow;
;     }
	s_cbranch_scc1 .Lmla_loop
	s_setprio 0
	s_waitcnt vmcnt(0)
	s_lshl_b64 s[6:7], s[10:11], 13
	v_ashrrev_i32_e32 v187, 31, v186
	v_lshl_add_u64 v[0:1], s[6:7], 0, v[186:187]
	v_or_b32_e32 v0, v0, v204
	v_mov_b32_e32 v2, s34
	v_mov_b32_e32 v3, s35
	v_mad_u64_u32 v[2:3], s[6:7], v0, s64, v[2:3]
	v_mad_i32_i24 v3, v1, s64, v3
	s_lshl_b32 s4, s52, 7
	v_lshl_add_u32 v12, v206, 1, s4
	v_mov_b32_e32 v13, 0
	v_lshl_add_u64 v[6:7], v[2:3], 0, v[12:13]
	s_mov_b64 s[6:7], 0x6058ec0
	v_lshl_add_u64 v[6:7], v[6:7], 0, s[6:7]
	global_load_dwordx2 v[64:65], v[6:7], off offset:0
	global_load_dwordx2 v[66:67], v[6:7], off offset:16
	global_load_dwordx2 v[68:69], v[6:7], off offset:32
	global_load_dwordx2 v[70:71], v[6:7], off offset:48
	global_load_dwordx2 v[72:73], v[6:7], off offset:64
	global_load_dwordx2 v[74:75], v[6:7], off offset:80
	global_load_dwordx2 v[76:77], v[6:7], off offset:96
	global_load_dwordx2 v[78:79], v[6:7], off offset:112
	v_readlane_b32 s6, v254, 49
	v_readlane_b32 s7, v254, 50
	v_lshlrev_b64 v[0:1], 11, v[0:1]
	s_nop 0
	v_lshl_add_u64 v[0:1], s[6:7], 0, v[0:1]
	v_lshl_add_u64 v[8:9], v[0:1], 0, v[12:13]
	v_cmp_nge_f32_e32 vcc, s94, v193
	s_nop 0
	s_cmp_lg_u64 vcc, 0
	s_cselect_b32 s24, 1, 0
	v_mov_b32_e32 v196, s24
	v_lshrrev_b32_e32 v197, 6, v184
	v_lshlrev_b32_e32 v197, 2, v197
	ds_write_b32 v197, v196 offset:0
	s_waitcnt lgkmcnt(0)
	s_barrier
	v_mov_b32_e32 v197, 0
	ds_read_b128 v[176:179], v197 offset:0
	ds_read_b128 v[180:183], v197 offset:16
	v_mov_b32_e32 v2, v192
	s_nop 1
	v_permlane32_swap_b32_e32 v192, v2
	v_add_f32_e32 v2, v192, v2
	v_div_scale_f32 v3, s[4:5], v2, v2, 1.0
	v_rcp_f32_e32 v4, v3
	s_nop 0
	v_fma_f32 v10, -v3, v4, 1.0
	v_fmac_f32_e32 v4, v10, v4
	v_div_scale_f32 v10, vcc, 1.0, v2, 1.0
	v_mul_f32_e32 v11, v10, v4
	v_fma_f32 v12, -v3, v11, v10
	v_fmac_f32_e32 v11, v12, v4
	v_fma_f32 v3, -v3, v11, v10
	s_nop 1
	v_div_fmas_f32 v3, v3, v4, v11
	v_div_fixup_f32 v2, v3, v2, 1.0
	s_waitcnt lgkmcnt(0)
	v_or3_b32 v196, v176, v177, v178
	v_or3_b32 v196, v196, v179, v180
	v_or3_b32 v196, v196, v181, v182
	v_or_b32_e32 v196, v196, v183
	s_nop 0
	v_readfirstlane_b32 s24, v196
	s_barrier
	s_cmp_lg_u32 s24, 0
	s_cbranch_scc1 .Lmla_slow
	s_waitcnt vmcnt(0)
	v_mul_f32_e32 v32, v32, v2
	v_mul_f32_e32 v33, v33, v2
	v_mul_f32_e32 v34, v34, v2
	v_mul_f32_e32 v35, v35, v2
	v_lshlrev_b32_e32 v196, 16, v64
	v_and_b32_e32 v197, 0xffff0000, v64
	v_mul_f32_e32 v32, v32, v196
	v_mul_f32_e32 v33, v33, v197
	v_lshlrev_b32_e32 v196, 16, v65
	v_and_b32_e32 v197, 0xffff0000, v65
	v_mul_f32_e32 v34, v34, v196
	v_mul_f32_e32 v35, v35, v197
	v_cvt_pk_bf16_f32 v32, v32, v33
	v_cvt_pk_bf16_f32 v33, v34, v35
	global_store_dwordx2 v[8:9], v[32:33], off offset:0
	v_mul_f32_e32 v36, v36, v2
	v_mul_f32_e32 v37, v37, v2
	v_mul_f32_e32 v38, v38, v2
	v_mul_f32_e32 v39, v39, v2
	v_lshlrev_b32_e32 v196, 16, v66
	v_and_b32_e32 v197, 0xffff0000, v66
	v_mul_f32_e32 v36, v36, v196
	v_mul_f32_e32 v37, v37, v197
	v_lshlrev_b32_e32 v196, 16, v67
	v_and_b32_e32 v197, 0xffff0000, v67
	v_mul_f32_e32 v38, v38, v196
	v_mul_f32_e32 v39, v39, v197
	v_cvt_pk_bf16_f32 v36, v36, v37
	v_cvt_pk_bf16_f32 v37, v38, v39
	global_store_dwordx2 v[8:9], v[36:37], off offset:16
	v_mul_f32_e32 v40, v40, v2
	v_mul_f32_e32 v41, v41, v2
	v_mul_f32_e32 v42, v42, v2
	v_mul_f32_e32 v43, v43, v2
	v_lshlrev_b32_e32 v196, 16, v68
	v_and_b32_e32 v197, 0xffff0000, v68
	v_mul_f32_e32 v40, v40, v196
	v_mul_f32_e32 v41, v41, v197
	v_lshlrev_b32_e32 v196, 16, v69
	v_and_b32_e32 v197, 0xffff0000, v69
	v_mul_f32_e32 v42, v42, v196
	v_mul_f32_e32 v43, v43, v197
	v_cvt_pk_bf16_f32 v40, v40, v41
	v_cvt_pk_bf16_f32 v41, v42, v43
	global_store_dwordx2 v[8:9], v[40:41], off offset:32
	v_mul_f32_e32 v44, v44, v2
	v_mul_f32_e32 v45, v45, v2
	v_mul_f32_e32 v46, v46, v2
	v_mul_f32_e32 v47, v47, v2
	v_lshlrev_b32_e32 v196, 16, v70
	v_and_b32_e32 v197, 0xffff0000, v70
	v_mul_f32_e32 v44, v44, v196
	v_mul_f32_e32 v45, v45, v197
	v_lshlrev_b32_e32 v196, 16, v71
	v_and_b32_e32 v197, 0xffff0000, v71
	v_mul_f32_e32 v46, v46, v196
	v_mul_f32_e32 v47, v47, v197
	v_cvt_pk_bf16_f32 v44, v44, v45
	v_cvt_pk_bf16_f32 v45, v46, v47
	global_store_dwordx2 v[8:9], v[44:45], off offset:48
	v_mul_f32_e32 v16, v16, v2
	v_mul_f32_e32 v17, v17, v2
	v_mul_f32_e32 v18, v18, v2
	v_mul_f32_e32 v19, v19, v2
	v_lshlrev_b32_e32 v196, 16, v72
	v_and_b32_e32 v197, 0xffff0000, v72
	v_mul_f32_e32 v16, v16, v196
	v_mul_f32_e32 v17, v17, v197
	v_lshlrev_b32_e32 v196, 16, v73
	v_and_b32_e32 v197, 0xffff0000, v73
	v_mul_f32_e32 v18, v18, v196
	v_mul_f32_e32 v19, v19, v197
	v_cvt_pk_bf16_f32 v16, v16, v17
	v_cvt_pk_bf16_f32 v17, v18, v19
	global_store_dwordx2 v[8:9], v[16:17], off offset:64
	v_mul_f32_e32 v20, v20, v2
	v_mul_f32_e32 v21, v21, v2
	v_mul_f32_e32 v22, v22, v2
	v_mul_f32_e32 v23, v23, v2
	v_lshlrev_b32_e32 v196, 16, v74
	v_and_b32_e32 v197, 0xffff0000, v74
	v_mul_f32_e32 v20, v20, v196
	v_mul_f32_e32 v21, v21, v197
	v_lshlrev_b32_e32 v196, 16, v75
	v_and_b32_e32 v197, 0xffff0000, v75
	v_mul_f32_e32 v22, v22, v196
	v_mul_f32_e32 v23, v23, v197
	v_cvt_pk_bf16_f32 v20, v20, v21
	v_cvt_pk_bf16_f32 v21, v22, v23
	global_store_dwordx2 v[8:9], v[20:21], off offset:80
	v_mul_f32_e32 v24, v24, v2
	v_mul_f32_e32 v25, v25, v2
	v_mul_f32_e32 v26, v26, v2
	v_mul_f32_e32 v27, v27, v2
	v_lshlrev_b32_e32 v196, 16, v76
	v_and_b32_e32 v197, 0xffff0000, v76
	v_mul_f32_e32 v24, v24, v196
	v_mul_f32_e32 v25, v25, v197
	v_lshlrev_b32_e32 v196, 16, v77
	v_and_b32_e32 v197, 0xffff0000, v77
	v_mul_f32_e32 v26, v26, v196
	v_mul_f32_e32 v27, v27, v197
	v_cvt_pk_bf16_f32 v24, v24, v25
	v_cvt_pk_bf16_f32 v25, v26, v27
	global_store_dwordx2 v[8:9], v[24:25], off offset:96
	v_mul_f32_e32 v28, v28, v2
	v_mul_f32_e32 v29, v29, v2
	v_mul_f32_e32 v30, v30, v2
	v_mul_f32_e32 v31, v31, v2
	v_lshlrev_b32_e32 v196, 16, v78
	v_and_b32_e32 v197, 0xffff0000, v78
	v_mul_f32_e32 v28, v28, v196
	v_mul_f32_e32 v29, v29, v197
	v_lshlrev_b32_e32 v196, 16, v79
	v_and_b32_e32 v197, 0xffff0000, v79
	v_mul_f32_e32 v30, v30, v196
	v_mul_f32_e32 v31, v31, v197
	v_cvt_pk_bf16_f32 v28, v28, v29
	v_cvt_pk_bf16_f32 v29, v30, v31
	global_store_dwordx2 v[8:9], v[28:29], off offset:112
	s_branch .LBB0_321

; #define LDS_BARRIER() asm volatile("s_waitcnt lgkmcnt(0)\n\ts_barrier" ::: "memory")
; template <int MODE>
; DI void attn_item(const Params& p, int layer, int bh, int qb, char* lds) {
;     ...
;       if (MODE == 1) {
;         const int rmax = k0 + 63 - q0w, rmin = k0 - (q0w + 31);
;         if (rmax <= -128) { cls = 1; cb = brel[224 - 128]; }
;         else if (rmin >= 128) { cls = 2; cb = brel[224 + 128]; }
;       }
;       const bool far = cls != 0;
;       if (cls != c0cls) { c0cls = cls; set_c0(cb - m); }
;     ...
;   __syncthreads();
;   gload(kt0, rkA, rvA); lstore(0, rkA, rvA);
;   if (nt > 1) gload(kt0 + 1, rkB, rvB);
;   LDS_BARRIER();
;   for (int t = 0; t < nt; t += 2) {
;     if (t + 2 < nt) gload(kt0 + t + 2, rkA, rvA);
;     compute(t, 0);
;     if (t + 1 < nt) lstore(1, rkB, rvB);
;     LDS_BARRIER();
;     if (t + 1 >= nt) break;
;     if (t + 3 < nt) gload(kt0 + t + 3, rkB, rvB);
;     compute(t + 1, 1);
;     if (t + 2 < nt) lstore(0, rkA, rvA);
;     LDS_BARRIER();
.Ldf_p_c0d:
	s_nop 11
	s_mov_b32 s62, 0
	ds_read_b64_tr_b16 v[222:223], v205 offset:54272
	ds_read_b64_tr_b16 v[224:225], v205 offset:55808
	ds_read_b64_tr_b16 v[226:227], v205 offset:54336
	ds_read_b64_tr_b16 v[228:229], v205 offset:55872
	ds_read_b128 v[230:233], v204 offset:2112
	v_readfirstlane_b32 s4, v184
	s_nop 3
	s_cmpk_ge_u32 s4, 0x100
	s_cbranch_scc0 .Ldf_prio
	s_setprio 1
.Ldf_prio:
.Ldf_loop:
	s_waitcnt vmcnt(0)
	ds_write_b128 v206, v[238:241] offset:45056
	ds_write_b128 v207, v[242:245] offset:32768
	buffer_load_dwordx4 v[246:249], v208, s[8:11], s93 offen
	buffer_load_dwordx4 v[250:253], v208, s[12:15], s28 offen
	s_add_u32 s93, s93, 0x2000
	s_add_u32 s28, s28, 0x2000
	s_cmp_ge_u32 s62, s24
	s_cbranch_scc0 .Ldf_s1_0
	s_cmp_lt_u32 s62, s25
	s_cbranch_scc1 .Ldf_fixa_0

; #define MFMA(a, b, c) __builtin_amdgcn_mfma_f32_32x32x16_bf16((a), (b), (c), 0, 0, 0)
; template <int MODE>
; DI void attn_item(const Params& p, int layer, int bh, int qb, char* lds) {
;     ...
;         if (first) rebase();
;         smpass();
;         if (!first && __any(!(ps <= PSLIM))) { rebase(); smpass(); }
;         l[mp] += ps;
;     ...
; #pragma unroll
;       for (int sub = 0; sub < 2; ++sub) {
;         s16x4 vv[8];
;         if (NMAP == 1) {
; #pragma unroll
;           for (int i = 0; i < 8; ++i) vv[i] = vpre[sub * 8 + i];
;         } else {
;           if (sub == 0) trread8<0>(vaddr, vv); else trread8<32 * VSTR>(vaddr, vv);
;         }
;         __builtin_amdgcn_s_setprio(1);
; #pragma unroll
;         for (int ks = 0; ks < 2; ++ks) {
; #pragma unroll
;           for (int dt = 0; dt < 2; ++dt) {
;             s16x4 lo = vv[ks * 4 + dt * 2], hi = vv[ks * 4 + dt * 2 + 1];
;             bf16x8 vf = __builtin_shufflevector(lo, hi, 0, 1, 2, 3, 4, 5, 6, 7);
; #pragma unroll
;             for (int mp = 0; mp < NMAP; ++mp) O[mp][dt] = MFMA(vf, __builtin_bit_cast(bf16x8, pk[mp][sub][ks]), O[mp][dt]);
;           }
;         }
;         __builtin_amdgcn_s_setprio(0);
;         __builtin_amdgcn_sched_barrier(0);
;       }
.Ldf_exit:
	s_setprio 0
	s_waitcnt vmcnt(0)
	s_waitcnt lgkmcnt(0)
	ds_read_b64_tr_b16 v[222:223], v205 offset:32768
	ds_read_b64_tr_b16 v[224:225], v205 offset:34304
	s_waitcnt lgkmcnt(0)
	v_mfma_f32_32x32x16_bf16 v[40:55], v[222:225], v[164:167], v[40:55]
	ds_read_b64_tr_b16 v[226:227], v205 offset:32832
	ds_read_b64_tr_b16 v[228:229], v205 offset:34368
	s_waitcnt lgkmcnt(0)
	v_mfma_f32_32x32x16_bf16 v[8:23], v[226:229], v[164:167], v[8:23]
	ds_read_b64_tr_b16 v[230:231], v205 offset:35840
	ds_read_b64_tr_b16 v[232:233], v205 offset:37376
	s_waitcnt lgkmcnt(0)
	v_mfma_f32_32x32x16_bf16 v[40:55], v[230:233], v[172:175], v[40:55]
	ds_read_b64_tr_b16 v[234:235], v205 offset:35904
	ds_read_b64_tr_b16 v[236:237], v205 offset:37440
	s_waitcnt lgkmcnt(0)
	v_mfma_f32_32x32x16_bf16 v[8:23], v[234:237], v[172:175], v[8:23]
	ds_read_b64_tr_b16 v[222:223], v205 offset:38912
	ds_read_b64_tr_b16 v[224:225], v205 offset:40448
	s_waitcnt lgkmcnt(0)
	v_mfma_f32_32x32x16_bf16 v[40:55], v[222:225], v[176:179], v[40:55]
	ds_read_b64_tr_b16 v[226:227], v205 offset:38976
	ds_read_b64_tr_b16 v[228:229], v205 offset:40512
	s_waitcnt lgkmcnt(0)
	v_mfma_f32_32x32x16_bf16 v[8:23], v[226:229], v[176:179], v[8:23]
	ds_read_b64_tr_b16 v[230:231], v205 offset:41984
	ds_read_b64_tr_b16 v[232:233], v205 offset:43520
	s_waitcnt lgkmcnt(0)
	v_mfma_f32_32x32x16_bf16 v[40:55], v[230:233], v[180:183], v[40:55]
	ds_read_b64_tr_b16 v[234:235], v205 offset:42048
	ds_read_b64_tr_b16 v[236:237], v205 offset:43584
	s_waitcnt lgkmcnt(0)
	v_mfma_f32_32x32x16_bf16 v[8:23], v[234:237], v[180:183], v[8:23]
	v_cmp_nge_f32_e32 vcc, s94, v201
	s_nop 0
	s_cmp_lg_u64 vcc, 0
	s_cselect_b32 s5, 1, 0
	v_mov_b32_e32 v196, s5
	v_lshrrev_b32_e32 v197, 6, v184
	v_lshlrev_b32_e32 v197, 2, v197
	v_add_u32_e32 v197, 66560, v197
	ds_write_b32 v197, v196
	s_waitcnt lgkmcnt(0)
	s_barrier
	v_mov_b32_e32 v197, 66560
	ds_read_b128 v[222:225], v197
	ds_read_b128 v[226:229], v197 offset:16
	s_waitcnt lgkmcnt(0)
	v_or3_b32 v196, v222, v223, v224
	v_or3_b32 v196, v196, v225, v226
	v_or3_b32 v196, v196, v227, v228
	v_or_b32_e32 v196, v196, v229
	s_nop 0
	v_readfirstlane_b32 s5, v196
	s_nop 11
	s_cmp_lg_u32 s5, 0
	s_cbranch_scc0 .LBB0_505
	s_barrier
	v_mov_b32_e32 v6, v184
	s_and_b32 s20, s60, 3
	s_lshl_b32 s23, s60, 5
	s_and_b32 s23, s23, 0x1f00
	s_mov_b64 s[4:5], -1
	s_mov_b64 s[8:9], -1
	s_branch .Ldiff_slow
